# P3: one workgroup barrier per two key tiles (DMA of two tiles after each), hand-written tile-loop head with scalar-base DMA addressing; on top of v97
# baseline (speedup 1.0000x reference)
.LBB0_531:
	s_lshl_b32 s0, s14, 2
	s_and_b32 s0, s0, 28
	v_sub_u32_e64 v2, s0, 1 clamp
	s_add_i32 s42, s12, s0
	s_max_u32 s43, s0, 4
	v_readfirstlane_b32 s0, v2
	s_bfe_u32 s71, s14, 0x40003
	s_min_u32 s0, s0, 24
	s_ashr_i32 s40, s14, 7
	s_sub_i32 s72, s0, s43
	s_lshl_b32 s0, s71, 8
	s_add_u32 s8, s68, s0
	s_addc_u32 s9, s69, 0
	s_add_u32 s10, s66, s0
	s_addc_u32 s11, s67, 0
	s_ashr_i32 s41, s40, 31
	s_lshl_b64 s[18:19], s[40:41], 11
	s_lshl_b32 s33, s42, 6
	s_add_u32 s18, s18, s33
	s_addc_u32 s19, s19, 0
	v_mov_b32_e32 v155, s19
	v_or_b32_e32 v154, s18, v146
	s_waitcnt lgkmcnt(0)
	v_lshlrev_b64 v[2:3], 12, v[154:155]
	s_lshl_b32 s18, s40, 8
	v_lshl_add_u64 v[2:3], s[20:21], 0, v[2:3]
	s_add_i32 s38, s18, 0x2000
	v_lshl_add_u64 v[2:3], v[2:3], 0, s[0:1]
	s_ashr_i32 s39, s38, 31
	v_lshl_add_u64 v[2:3], v[2:3], 0, v[152:153]
	s_lshl_b64 s[74:75], s[38:39], 12
	s_ashr_i32 s19, s18, 31
	global_load_dwordx4 v[82:85], v[2:3], off nt
	global_load_dwordx4 v[86:89], v[2:3], off offset:32 nt
	global_load_dwordx4 v[90:93], v[2:3], off offset:64 nt
	global_load_dwordx4 v[94:97], v[2:3], off offset:96 nt
	global_load_dwordx4 v[98:101], v[2:3], off offset:128 nt
	global_load_dwordx4 v[102:105], v[2:3], off offset:160 nt
	global_load_dwordx4 v[106:109], v[2:3], off offset:192 nt
	global_load_dwordx4 v[110:113], v[2:3], off offset:224 nt
	v_lshl_add_u64 v[2:3], s[74:75], 0, v[148:149]
	s_lshl_b64 s[18:19], s[18:19], 12
	s_mov_b32 m0, s15
	v_lshl_add_u64 v[4:5], s[10:11], 0, v[2:3]
	s_add_u32 s74, s18, 0x2020000
	global_load_lds_dwordx4 v[4:5], off
	v_lshl_add_u64 v[2:3], s[8:9], 0, v[2:3]
	s_mov_b32 m0, s24
	s_addc_u32 s75, s19, 0
	global_load_lds_dwordx4 v[2:3], off
	v_lshl_add_u64 v[2:3], s[74:75], 0, v[148:149]
	v_lshl_add_u64 v[4:5], s[10:11], 0, v[2:3]
	s_mov_b32 m0, s25
	s_add_u32 s74, s18, 0x2040000
	global_load_lds_dwordx4 v[4:5], off
	v_lshl_add_u64 v[2:3], s[8:9], 0, v[2:3]
	s_mov_b32 m0, s35
	s_addc_u32 s75, s19, 0
	global_load_lds_dwordx4 v[2:3], off
	v_lshl_add_u64 v[2:3], s[74:75], 0, v[148:149]
	v_lshl_add_u64 v[4:5], s[10:11], 0, v[2:3]
	s_mov_b32 m0, s46
	s_add_u32 s74, s18, 0x2060000
	global_load_lds_dwordx4 v[4:5], off
	v_lshl_add_u64 v[2:3], s[8:9], 0, v[2:3]
	s_mov_b32 m0, s47
	s_addc_u32 s75, s19, 0
	global_load_lds_dwordx4 v[2:3], off
	v_lshl_add_u64 v[2:3], s[74:75], 0, v[148:149]
	v_lshl_add_u64 v[4:5], s[10:11], 0, v[2:3]
	s_mov_b32 m0, s57
	s_add_u32 s18, s18, 0x2080000
	global_load_lds_dwordx4 v[4:5], off
	v_lshl_add_u64 v[2:3], s[8:9], 0, v[2:3]
	s_mov_b32 m0, s60
	s_addc_u32 s19, s19, 0
	global_load_lds_dwordx4 v[2:3], off
	v_lshl_add_u64 v[2:3], s[18:19], 0, v[148:149]
	v_lshl_add_u64 v[4:5], s[10:11], 0, v[2:3]
	s_mov_b32 m0, s61
	v_lshl_add_u64 v[2:3], s[8:9], 0, v[2:3]
	s_mov_b32 m0, s63
	s_cmp_lt_i32 s72, -15
	s_cbranch_scc1 .LBB0_547
	s_max_i32 s0, s42, 4
	s_add_i32 s0, s0, -4
	s_mul_i32 s18, s71, 15
	s_min_u32 s0, s0, 24
	s_sub_i32 s18, s18, s42
	s_add_i32 s18, s18, s0
	v_mov_b32_e32 v50, v151
	v_mov_b32_e32 v51, v151
	s_lshl_b32 s72, s72, 1
	s_mulk_i32 s18, 0x7c
	v_mov_b32_e32 v52, v151
	v_mov_b32_e32 v53, v151
	v_mov_b32_e32 v54, v151
	v_mov_b32_e32 v55, v151
	v_mov_b32_e32 v56, v151
	v_mov_b32_e32 v57, v151
	v_mov_b32_e32 v58, v151
	v_mov_b32_e32 v59, v151
	v_mov_b32_e32 v60, v151
	v_mov_b32_e32 v61, v151
	v_mov_b32_e32 v62, v151
	v_mov_b32_e32 v63, v151
	v_mov_b32_e32 v64, v151
	v_mov_b32_e32 v65, v151
	v_mov_b64_e32 v[34:35], v[50:51]
	v_mov_b64_e32 v[18:19], v[50:51]
	v_mov_b64_e32 v[2:3], v[50:51]
	s_add_i32 s39, s43, -4
	s_add_i32 s72, s72, 31
	s_lshl_b32 s73, s40, 11
	s_add_i32 s74, s0, 8
	v_add_u32_e32 v176, s18, v172
	s_mov_b32 s75, 0
	s_mov_b32 s76, 4
	v_mov_b32_e32 v177, 0xff800000
	v_mov_b32_e32 v175, 0
	v_mov_b64_e32 v[36:37], v[52:53]
	v_mov_b64_e32 v[38:39], v[54:55]
	v_mov_b64_e32 v[40:41], v[56:57]
	v_mov_b64_e32 v[42:43], v[58:59]
	v_mov_b64_e32 v[44:45], v[60:61]
	v_mov_b64_e32 v[46:47], v[62:63]
	v_mov_b64_e32 v[48:49], v[64:65]
	v_mov_b64_e32 v[20:21], v[52:53]
	v_mov_b64_e32 v[22:23], v[54:55]
	v_mov_b64_e32 v[24:25], v[56:57]
	v_mov_b64_e32 v[26:27], v[58:59]
	v_mov_b64_e32 v[28:29], v[60:61]
	v_mov_b64_e32 v[30:31], v[62:63]
	v_mov_b64_e32 v[32:33], v[64:65]
	v_mov_b64_e32 v[4:5], v[52:53]
	v_mov_b64_e32 v[6:7], v[54:55]
	v_mov_b64_e32 v[8:9], v[56:57]
	v_mov_b64_e32 v[10:11], v[58:59]
	v_mov_b64_e32 v[12:13], v[60:61]
	v_mov_b64_e32 v[14:15], v[62:63]
	v_mov_b64_e32 v[16:17], v[64:65]
	s_mov_b32 s77, 0
	s_mov_b32 s78, 0
	s_mov_b32 s100, s38
	s_lshl_b32 s101, s39, 6
	s_add_i32 s101, s101, s73
	s_addk_i32 s101, 0xff00
	s_waitcnt vmcnt(0)
.LBB0_533:
	s_bitcmp1_b32 s78, 0
	s_cbranch_scc1 .Lp3_odd
	s_waitcnt vmcnt(4)
	s_barrier
	s_add_i32 s18, s78, 4
	s_min_i32 s18, s18, s72
	s_cmp_lt_i32 s18, 8
	s_cselect_b32 s19, s100, s101
	s_lshl_b32 s18, s18, 5
	s_add_i32 s40, s19, s18
	s_ashr_i32 s41, s40, 31
	s_lshl_b64 s[18:19], s[40:41], 12
	s_add_u32 s40, s10, s18
	s_addc_u32 s41, s11, s19
	s_add_u32 s18, s8, s18
	s_addc_u32 s19, s9, s19
	s_lshl_b32 s33, s76, 14
	s_add_i32 s33, s13, s33
	s_add_i32 m0, s33, 0x8000
	s_nop 0
	global_load_lds_dwordx4 v148, s[40:41]
	s_add_i32 m0, s33, 0xa000
	s_nop 0
	global_load_lds_dwordx4 v148, s[18:19]
	s_add_i32 s18, s78, 5
	s_min_i32 s18, s18, s72
	s_cmp_lt_i32 s18, 8
	s_cselect_b32 s19, s100, s101
	s_lshl_b32 s18, s18, 5
	s_add_i32 s40, s19, s18
	s_ashr_i32 s41, s40, 31
	s_lshl_b64 s[18:19], s[40:41], 12
	s_add_u32 s40, s10, s18
	s_addc_u32 s41, s11, s19
	s_add_u32 s18, s8, s18
	s_addc_u32 s19, s9, s19
	s_add_i32 s33, s76, 1
	s_cmp_lg_u32 s33, 6
	s_cselect_b32 s33, s33, 0
	s_lshl_b32 s33, s33, 14
	s_add_i32 s33, s13, s33
	s_add_i32 m0, s33, 0x8000
	s_nop 0
	global_load_lds_dwordx4 v148, s[40:41]
	s_add_i32 m0, s33, 0xa000
	s_nop 0
	global_load_lds_dwordx4 v148, s[18:19]
.Lp3_odd:
	s_cmp_gt_u32 s78, 7
	s_cselect_b64 s[40:41], -1, 0
	s_add_i32 s18, s78, -8
	s_ashr_i32 s79, s18, 1
	s_add_i32 s79, s79, s39
	s_cmp_lt_u32 s78, 8
	s_cbranch_scc1 .Lp3_act
	s_cmp_lt_i32 s79, s0
	s_cbranch_scc1 .LBB0_545
	s_cmp_ge_i32 s79, s74
	s_cbranch_scc1 .LBB0_545
.Lp3_act:
	s_lshl_b32 s18, s77, 14
	s_add_i32 s19, s18, 0x8000
	v_add3_u32 v198, s18, v147, v1
	ds_read_b128 v[198:201], v198 offset:32768
	v_add3_u32 v202, s18, v156, v1
	ds_read_b128 v[202:205], v202 offset:32768
	v_add3_u32 v206, s18, v157, v1
	ds_read_b128 v[206:209], v206 offset:32768
	v_add3_u32 v210, s18, v158, v1
	ds_read_b128 v[210:213], v210 offset:32768
	v_add3_u32 v214, s18, v159, v1
	ds_read_b128 v[214:217], v214 offset:32768
	v_add3_u32 v218, s18, v160, v1
	ds_read_b128 v[218:221], v218 offset:32768
	v_add_u32_e32 v180, s19, v163
	v_add_u32_e32 v181, s19, v164
	v_add_u32_e32 v182, s19, v165
	v_add_u32_e32 v183, s19, v166
	v_add_u32_e32 v184, s19, v167
	v_add_u32_e32 v185, s19, v168
	v_add_u32_e32 v186, s19, v169
	v_add_u32_e32 v187, s19, v170
	v_add3_u32 v188, s18, v161, v1
	v_add3_u32 v189, s18, v162, v1
	ds_read_b64_tr_b16 v[142:143], v180
	ds_read_b64_tr_b16 v[126:127], v180 offset:4096
	ds_read_b64_tr_b16 v[138:139], v181
	ds_read_b64_tr_b16 v[122:123], v181 offset:4096
	s_andn2_b64 vcc, exec, s[40:41]
	s_waitcnt lgkmcnt(9)
	s_cbranch_vccnz .Lp3_m0ctx
	s_bitcmp1_b32 s75, 5
	s_cbranch_scc1 .Lp3_m0k1
	v_mfma_f32_32x32x16_bf16 v[66:81], v[198:201], v[82:85], v[222:237]
	s_branch .Lp3_m0join
